# R3 phase start: conservative vmcnt(0) waits behind the first LDS-DMA issue counted; first-stage DMA wait and barrier deferred behind the q loads
# baseline (speedup 1.0000x reference)
.LBB0_1078:
	s_ashr_i32 s10, s0, 6
	v_and_b32_e32 v1, 63, v0
	s_lshl_b32 s20, s10, 10
	v_lshl_or_b32 v4, v1, 4, s20
	s_mov_b32 s8, 0x78787879
	v_mul_hi_i32 v2, v4, s8
	v_lshrrev_b32_e32 v3, 31, v2
	v_ashrrev_i32_e32 v2, 8, v2
	v_add_u32_e32 v147, v2, v3
	v_mul_i32_i24_e32 v2, 0x220, v147
	v_sub_u32_e32 v2, v4, v2
	s_movk_i32 s9, 0x200
	v_cmp_gt_i32_e32 vcc, s9, v2
	s_ashr_i32 s1, s3, 1
	s_bfe_u32 s0, s3, 0x30002
	v_cndmask_b32_e32 v184, 0, v2, vcc
	v_add_u32_e32 v2, 0x2000, v4
	v_mul_hi_i32 v3, v2, s8
	v_lshrrev_b32_e32 v5, 31, v3
	v_ashrrev_i32_e32 v3, 8, v3
	v_add_u32_e32 v185, v3, v5
	v_mul_i32_i24_e32 v3, 0x220, v185
	v_sub_u32_e32 v2, v2, v3
	v_cmp_gt_i32_e32 vcc, s9, v2
	s_and_b32 s1, s1, -16
	s_or_b32 s0, s1, s0
	v_cndmask_b32_e32 v186, 0, v2, vcc
	v_add_u32_e32 v2, 0x4000, v4
	v_mul_hi_i32 v3, v2, s8
	v_lshrrev_b32_e32 v5, 31, v3
	v_ashrrev_i32_e32 v3, 8, v3
	v_add_u32_e32 v187, v3, v5
	v_mul_i32_i24_e32 v3, 0x220, v187
	s_ashr_i32 s1, s0, 31
	v_sub_u32_e32 v2, v2, v3
	s_lshl_b64 s[4:5], s[0:1], 17
	v_cmp_gt_i32_e32 vcc, s9, v2
	s_add_u32 s4, s46, s4
	s_addc_u32 s5, s47, s5
	v_cndmask_b32_e32 v188, 0, v2, vcc
	v_add_u32_e32 v2, 0x6000, v4
	s_or_b32 s0, s0, 8
	v_mul_hi_i32 v3, v2, s8
	s_ashr_i32 s1, s0, 31
	v_lshrrev_b32_e32 v5, 31, v3
	v_ashrrev_i32_e32 v3, 8, v3
	s_lshl_b64 s[0:1], s[0:1], 17
	v_add_u32_e32 v189, v3, v5
	s_add_u32 s6, s46, s0
	v_mul_i32_i24_e32 v3, 0x220, v189
	s_addc_u32 s7, s47, s1
	v_sub_u32_e32 v2, v2, v3
	s_cmp_lt_i32 s10, 2
	s_waitcnt vmcnt(10)
	v_lshl_add_u32 v132, v147, 9, v184
	v_cmp_gt_i32_e32 vcc, s9, v2
	s_cselect_b64 s[0:1], -1, 0
	v_ashrrev_i32_e32 v133, 31, v132
	s_add_i32 s21, s20, 0
	v_cndmask_b32_e32 v190, 0, v2, vcc
	v_lshl_add_u64 v[2:3], s[4:5], 0, v[132:133]
	s_mov_b32 m0, s21
	s_add_i32 s48, s21, 0x8800
	v_lshl_add_u32 v134, v185, 9, v186
	s_barrier
	global_load_lds_dwordx4 v[2:3], off
	v_lshl_add_u64 v[2:3], s[6:7], 0, v[132:133]
	s_mov_b32 m0, s48
	v_ashrrev_i32_e32 v135, 31, v134
	s_add_i32 s49, s21, 0x2000
	global_load_lds_dwordx4 v[2:3], off
	v_lshl_add_u64 v[2:3], s[4:5], 0, v[134:135]
	s_mov_b32 m0, s49
	s_add_i32 s62, s21, 0xa800
	s_waitcnt vmcnt(2)
	v_lshl_add_u32 v136, v187, 9, v188
	global_load_lds_dwordx4 v[2:3], off
	v_lshl_add_u64 v[2:3], s[6:7], 0, v[134:135]
	s_mov_b32 m0, s62
	v_ashrrev_i32_e32 v137, 31, v136
	s_add_i32 s63, s21, 0x4000
	global_load_lds_dwordx4 v[2:3], off
	v_lshl_add_u64 v[2:3], s[4:5], 0, v[136:137]
	s_mov_b32 m0, s63
	s_add_i32 s64, s21, 0xc800
	v_lshl_add_u32 v138, v189, 9, v190
	global_load_lds_dwordx4 v[2:3], off
	v_lshl_add_u64 v[2:3], s[6:7], 0, v[136:137]
	s_mov_b32 m0, s64
	v_ashrrev_i32_e32 v139, 31, v138
	s_add_i32 s65, s21, 0x6000
	global_load_lds_dwordx4 v[2:3], off
	v_lshl_add_u64 v[2:3], s[4:5], 0, v[138:139]
	s_mov_b32 m0, s65
	s_add_i32 s66, s21, 0xe800
	global_load_lds_dwordx4 v[2:3], off
	v_lshl_add_u64 v[2:3], s[6:7], 0, v[138:139]
	s_mov_b32 m0, s66
	s_nop 0
	global_load_lds_dwordx4 v[2:3], off
	v_add_u32_e32 v2, 0x8000, v4
	v_mul_hi_i32 v3, v2, s8
	v_lshrrev_b32_e32 v4, 31, v3
	v_ashrrev_i32_e32 v3, 8, v3
	v_add_u32_e32 v191, v3, v4
	v_mul_i32_i24_e32 v3, 0x220, v191
	v_sub_u32_e32 v2, v2, v3
	v_cmp_gt_i32_e32 vcc, s9, v2
	s_nop 1
	v_cndmask_b32_e32 v192, 0, v2, vcc
	s_and_b64 vcc, exec, s[0:1]
	v_lshl_add_u32 v140, v191, 9, v192
	s_cbranch_vccnz .LBB0_1080
	v_ashrrev_i32_e32 v141, 31, v140
	s_add_i32 s67, s20, 0x8000
	s_cbranch_execz .LBB0_1081
	s_branch .LBB0_1082

.LBB0_1082:
	v_lshrrev_b32_e32 v3, 4, v1
	v_lshlrev_b32_e32 v1, 3, v1
	v_lshlrev_b32_e32 v146, 2, v3
	v_and_b32_e32 v195, 24, v1
	v_or_b32_e32 v1, 1, v146
	v_cvt_f32_ubyte0_e32 v197, v1
	v_or_b32_e32 v1, 2, v146
	v_cvt_f32_ubyte0_e32 v198, v1
	v_or_b32_e32 v1, 3, v146
	v_cvt_f32_ubyte0_e32 v199, v1
	v_or_b32_e32 v1, 16, v146
	v_cvt_f32_ubyte0_e32 v200, v1
	v_or_b32_e32 v1, 17, v146
	v_cvt_f32_ubyte0_e32 v201, v1
	v_or_b32_e32 v1, 18, v146
	v_cvt_f32_ubyte0_e32 v202, v1
	v_or_b32_e32 v1, 19, v146
	v_cvt_f32_ubyte0_e32 v203, v1
	v_or_b32_e32 v1, 32, v146
	v_cvt_f32_ubyte0_e32 v204, v1
	v_or_b32_e32 v1, 33, v146
	v_cvt_f32_ubyte0_e32 v205, v1
	v_or_b32_e32 v1, 34, v146
	v_cvt_f32_ubyte0_e32 v206, v1
	v_or_b32_e32 v1, 35, v146
	v_cvt_f32_ubyte0_e32 v207, v1
	v_or_b32_e32 v1, 48, v146
	s_add_u32 s40, s28, 0xba80000
	v_cvt_f32_ubyte0_e32 v208, v1
	v_or_b32_e32 v1, 49, v146
	s_addc_u32 s41, s29, 0
	s_lshl_b32 s68, s10, 4
	v_cvt_f32_ubyte0_e32 v209, v1
	v_or_b32_e32 v1, 50, v146
	s_ashr_i32 s4, s68, 31
	v_cvt_f32_ubyte0_e32 v210, v1
	v_or_b32_e32 v1, 51, v146
	v_and_b32_e32 v193, 15, v0
	v_mov_b32_e32 v143, s4
	v_cvt_f32_ubyte0_e32 v211, v1
	s_movk_i32 s4, 0x220
	v_mov_b32_e32 v1, 0x2200
	v_mad_u32_u24 v214, v193, s4, v1
	v_mov_b32_e32 v1, 0x4400
	v_mad_u32_u24 v215, v193, s4, v1
	v_mov_b32_e32 v1, 0x6600
	s_add_i32 s5, 0, 0x11000
	s_add_i32 s6, 0, 0x19800
	s_lshl_b32 s69, s3, 7
	s_lshl_b32 s70, s30, 7
	s_waitcnt vmcnt(8)
	v_lshlrev_b32_e32 v2, 3, v3
	v_mad_u32_u24 v216, v193, s4, v1
	v_mov_b32_e32 v1, s5
	v_mov_b32_e32 v3, s6
	s_add_u32 s71, s28, 0x5aa0000
	v_or_b32_e32 v142, s68, v193
	v_and_b32_e32 v194, 48, v0
	v_bfe_u32 v0, v0, 2, 4
	v_mul_u32_u24_e32 v212, 0x220, v193
	v_mad_u32_u24 v1, v193, s4, v1
	v_mad_u32_u24 v3, v193, s4, v3
	v_add_u32_e32 v4, s5, v214
	v_add_u32_e32 v5, s6, v214
	v_add_u32_e32 v6, s5, v215
	v_add_u32_e32 v7, s6, v215
	v_add_u32_e32 v8, s5, v216
	v_add_u32_e32 v9, s6, v216
	v_lshl_add_u32 v148, v147, 11, v184
	v_lshl_add_u32 v150, v185, 11, v186
	v_lshl_add_u32 v152, v187, 11, v188
	v_lshl_add_u32 v154, v189, 11, v190
	v_lshl_add_u32 v156, v191, 11, v192
	s_addc_u32 s72, s29, 0
	s_add_i32 s82, s67, 0
	v_mov_b32_e32 v145, 0
	v_cvt_f32_ubyte0_e32 v196, v146
	s_mov_b32 s43, 0
	v_add3_u32 v213, 0, v212, v194
	v_add_u32_e32 v217, s5, v194
	v_add_u32_e32 v218, s6, v194
	v_ashrrev_i32_e32 v149, 31, v148
	v_ashrrev_i32_e32 v151, 31, v150
	v_ashrrev_i32_e32 v153, 31, v152
	v_ashrrev_i32_e32 v155, 31, v154
	v_ashrrev_i32_e32 v157, 31, v156
	v_mul_u32_u24_e32 v219, 0x220, v0
	v_sub_u32_e32 v220, v142, v146
	s_lshl_b32 s73, s3, 3
	v_lshlrev_b32_e32 v144, 1, v2
	s_add_i32 s74, s21, 0x11000
	s_add_i32 s75, s21, 0x19800
	s_add_i32 s76, s21, 0x13000
	s_add_i32 s77, s21, 0x1b800
	s_add_i32 s78, s21, 0x15000
	s_add_i32 s79, s21, 0x1d800
	s_add_i32 s80, s21, 0x17000
	s_add_i32 s81, s21, 0x1f800
	s_add_i32 s83, s82, 0x11000
	s_add_i32 s84, s82, 0x19800
	s_mov_b32 s85, 0xbfb8aa3b
	s_mov_b32 s86, 0x42ce8ed0
	s_mov_b32 s87, 0xc2b17218
	s_mov_b32 s88, 0x7f800000
	s_mov_b32 s89, 0x3f2aaaab
	v_mov_b32_e32 v221, 0x3ecc95a3
	s_mov_b32 s90, 0x3f317218
	s_mov_b32 s91, 0x33800000
	v_mbcnt_hi_u32_b32 v222, -1, v248
	v_mov_b32_e32 v223, 0x358637bd
	v_mov_b32_e32 v224, 0x7f800000
	v_mov_b32_e32 v158, 0x3f317218
	v_add_u32_e32 v225, v1, v194
	v_add_u32_e32 v226, v3, v194
	v_add_u32_e32 v227, v4, v194
	v_add_u32_e32 v228, v5, v194
	v_add_u32_e32 v229, v6, v194
	v_add_u32_e32 v232, v7, v194
	v_add_u32_e32 v233, v8, v194
	v_add_u32_e32 v234, v9, v194
	s_waitcnt lgkmcnt(0)
	s_branch .LBB0_1084

.LBB0_1086:
	v_mul_f32_e32 v34, 0xbfb8aa3b, v33
	v_rndne_f32_e32 v35, v34
	v_sub_f32_e32 v36, v34, v35
	v_fma_f32 v34, v33, s85, -v34
	v_fmac_f32_e32 v34, 0xb2a5705f, v33
	v_add_f32_e32 v34, v36, v34
	v_exp_f32_e32 v34, v34
	v_cvt_i32_f32_e32 v35, v35
	v_cmp_nlt_f32_e32 vcc, s86, v33
	s_add_u32 s58, s42, 0x10000
	s_addc_u32 s59, s96, 0
	v_ldexp_f32 v34, v34, v35
	v_cndmask_b32_e32 v34, 0, v34, vcc
	v_cmp_ngt_f32_e32 vcc, s87, v33
	s_add_u32 s60, s97, 0x10000
	s_addc_u32 s61, s18, 0
	v_cndmask_b32_e32 v79, v224, v34, vcc
	v_add_f32_e32 v159, 1.0, v79
	v_frexp_mant_f32_e32 v33, v159
	v_cmp_gt_f32_e64 s[16:17], s89, v33
	v_mul_f32_e32 v33, 0xbfb8aa3b, v32
	v_rndne_f32_e32 v34, v33
	v_sub_f32_e32 v35, v33, v34
	v_fma_f32 v33, v32, s85, -v33
	v_fmac_f32_e32 v33, 0xb2a5705f, v32
	v_add_f32_e32 v33, v35, v33
	v_exp_f32_e32 v33, v33
	v_cvt_i32_f32_e32 v34, v34
	v_cmp_nlt_f32_e32 vcc, s86, v32
	s_mov_b32 m0, s21
	v_cmp_neq_f32_e64 s[10:11], s88, v79
	v_ldexp_f32 v33, v33, v34
	v_cndmask_b32_e32 v33, 0, v33, vcc
	v_cmp_ngt_f32_e32 vcc, s87, v32
	v_cmp_lt_f32_e64 s[12:13], |v79|, s91
	s_nop 0
	v_cndmask_b32_e32 v78, v224, v33, vcc
	v_add_f32_e32 v162, 1.0, v78
	v_frexp_mant_f32_e32 v32, v162
	v_cmp_gt_f32_e64 s[14:15], s89, v32
	s_barrier
	ds_read_b128 v[80:83], v213
	ds_read_b128 v[84:87], v213 offset:34816
	ds_read_b128 v[88:91], v213 offset:64
	ds_read_b128 v[92:95], v213 offset:34880
	ds_read_b128 v[96:99], v213 offset:128
	ds_read_b128 v[100:103], v213 offset:34944
	ds_read_b128 v[104:107], v213 offset:192
	s_waitcnt lgkmcnt(6)
	v_mfma_f32_16x16x32_bf16 v[32:35], v[80:83], v[0:3], 0
	ds_read_b128 v[108:111], v213 offset:35008
	v_cmp_neq_f32_e64 s[6:7], s88, v78
	s_waitcnt lgkmcnt(6)
	v_mfma_f32_16x16x32_bf16 v[36:39], v[84:87], v[0:3], 0
	ds_read_b128 v[80:83], v213 offset:256
	v_cmp_lt_f32_e64 s[8:9], |v78|, s91
	s_waitcnt lgkmcnt(6)
	v_mfma_f32_16x16x32_bf16 v[32:35], v[88:91], v[4:7], v[32:35]
	ds_read_b128 v[84:87], v213 offset:35072
	s_and_b64 vcc, exec, s[4:5]
	s_waitcnt lgkmcnt(6)
	v_mfma_f32_16x16x32_bf16 v[36:39], v[92:95], v[4:7], v[36:39]
	ds_read_b128 v[88:91], v213 offset:320
	s_waitcnt lgkmcnt(6)
	v_mfma_f32_16x16x32_bf16 v[32:35], v[96:99], v[8:11], v[32:35]
	ds_read_b128 v[92:95], v213 offset:35136
	s_waitcnt lgkmcnt(6)
	v_mfma_f32_16x16x32_bf16 v[36:39], v[100:103], v[8:11], v[36:39]
	ds_read_b128 v[96:99], v213 offset:384
	s_waitcnt lgkmcnt(6)
	v_mfma_f32_16x16x32_bf16 v[32:35], v[104:107], v[12:15], v[32:35]
	ds_read_b128 v[100:103], v213 offset:35200
	s_waitcnt lgkmcnt(6)
	v_mfma_f32_16x16x32_bf16 v[36:39], v[108:111], v[12:15], v[36:39]
	ds_read_b128 v[104:107], v213 offset:448
	s_waitcnt lgkmcnt(6)
	v_mfma_f32_16x16x32_bf16 v[32:35], v[80:83], v[16:19], v[32:35]
	ds_read_b128 v[108:111], v213 offset:35264
	s_waitcnt lgkmcnt(6)
	v_mfma_f32_16x16x32_bf16 v[36:39], v[84:87], v[16:19], v[36:39]
	ds_read_b128 v[80:83], v213 offset:8704
	s_waitcnt lgkmcnt(6)
	v_mfma_f32_16x16x32_bf16 v[32:35], v[88:91], v[20:23], v[32:35]
	ds_read_b128 v[84:87], v213 offset:43520
	s_waitcnt lgkmcnt(6)
	v_mfma_f32_16x16x32_bf16 v[36:39], v[92:95], v[20:23], v[36:39]
	ds_read_b128 v[88:91], v213 offset:8768
	s_waitcnt lgkmcnt(6)
	v_mfma_f32_16x16x32_bf16 v[32:35], v[96:99], v[24:27], v[32:35]
	ds_read_b128 v[92:95], v213 offset:43584
	s_waitcnt lgkmcnt(6)
	v_mfma_f32_16x16x32_bf16 v[36:39], v[100:103], v[24:27], v[36:39]
	ds_read_b128 v[96:99], v213 offset:8832
	s_waitcnt lgkmcnt(6)
	v_mfma_f32_16x16x32_bf16 v[32:35], v[104:107], v[28:31], v[32:35]
	ds_read_b128 v[100:103], v213 offset:43648
	s_waitcnt lgkmcnt(6)
	v_mfma_f32_16x16x32_bf16 v[36:39], v[108:111], v[28:31], v[36:39]
	ds_read_b128 v[104:107], v213 offset:8896
	s_waitcnt lgkmcnt(6)
	v_mfma_f32_16x16x32_bf16 v[40:43], v[80:83], v[0:3], 0
	ds_read_b128 v[108:111], v213 offset:43712
	s_waitcnt lgkmcnt(6)
	v_mfma_f32_16x16x32_bf16 v[44:47], v[84:87], v[0:3], 0
	ds_read_b128 v[80:83], v213 offset:8960
	s_waitcnt lgkmcnt(6)
	v_mfma_f32_16x16x32_bf16 v[40:43], v[88:91], v[4:7], v[40:43]
	ds_read_b128 v[84:87], v213 offset:43776
	s_waitcnt lgkmcnt(6)
	v_mfma_f32_16x16x32_bf16 v[44:47], v[92:95], v[4:7], v[44:47]
	ds_read_b128 v[88:91], v213 offset:9024
	s_waitcnt lgkmcnt(6)
	v_mfma_f32_16x16x32_bf16 v[40:43], v[96:99], v[8:11], v[40:43]
	ds_read_b128 v[92:95], v213 offset:43840
	s_waitcnt lgkmcnt(6)
	v_mfma_f32_16x16x32_bf16 v[44:47], v[100:103], v[8:11], v[44:47]
	ds_read_b128 v[96:99], v213 offset:9088
	s_waitcnt lgkmcnt(6)
	v_mfma_f32_16x16x32_bf16 v[40:43], v[104:107], v[12:15], v[40:43]
	ds_read_b128 v[100:103], v213 offset:43904
	s_waitcnt lgkmcnt(6)
	v_mfma_f32_16x16x32_bf16 v[44:47], v[108:111], v[12:15], v[44:47]
	ds_read_b128 v[104:107], v213 offset:9152
	s_waitcnt lgkmcnt(6)
	v_mfma_f32_16x16x32_bf16 v[40:43], v[80:83], v[16:19], v[40:43]
	ds_read_b128 v[108:111], v213 offset:43968
	s_waitcnt lgkmcnt(6)
	v_mfma_f32_16x16x32_bf16 v[44:47], v[84:87], v[16:19], v[44:47]
	ds_read_b128 v[80:83], v213 offset:17408
	s_waitcnt lgkmcnt(6)
	v_mfma_f32_16x16x32_bf16 v[40:43], v[88:91], v[20:23], v[40:43]
	ds_read_b128 v[84:87], v213 offset:52224
	s_waitcnt lgkmcnt(6)
	v_mfma_f32_16x16x32_bf16 v[44:47], v[92:95], v[20:23], v[44:47]
	ds_read_b128 v[88:91], v213 offset:17472
	s_waitcnt lgkmcnt(6)
	v_mfma_f32_16x16x32_bf16 v[40:43], v[96:99], v[24:27], v[40:43]
	ds_read_b128 v[92:95], v213 offset:52288
	s_waitcnt lgkmcnt(6)
	v_mfma_f32_16x16x32_bf16 v[44:47], v[100:103], v[24:27], v[44:47]
	ds_read_b128 v[96:99], v213 offset:17536
	s_waitcnt lgkmcnt(6)
	v_mfma_f32_16x16x32_bf16 v[40:43], v[104:107], v[28:31], v[40:43]
	ds_read_b128 v[100:103], v213 offset:52352
	s_waitcnt lgkmcnt(6)
	v_mfma_f32_16x16x32_bf16 v[44:47], v[108:111], v[28:31], v[44:47]
	ds_read_b128 v[104:107], v213 offset:17600
	s_waitcnt lgkmcnt(6)
	v_mfma_f32_16x16x32_bf16 v[48:51], v[80:83], v[0:3], 0
	ds_read_b128 v[108:111], v213 offset:52416
	s_waitcnt lgkmcnt(6)
	v_mfma_f32_16x16x32_bf16 v[52:55], v[84:87], v[0:3], 0
	ds_read_b128 v[80:83], v213 offset:17664
	s_waitcnt lgkmcnt(6)
	v_mfma_f32_16x16x32_bf16 v[48:51], v[88:91], v[4:7], v[48:51]
	ds_read_b128 v[84:87], v213 offset:52480
	s_waitcnt lgkmcnt(6)
	v_mfma_f32_16x16x32_bf16 v[52:55], v[92:95], v[4:7], v[52:55]
	ds_read_b128 v[88:91], v213 offset:17728
	s_waitcnt lgkmcnt(6)
	v_mfma_f32_16x16x32_bf16 v[48:51], v[96:99], v[8:11], v[48:51]
	ds_read_b128 v[92:95], v213 offset:52544
	s_waitcnt lgkmcnt(6)
	v_mfma_f32_16x16x32_bf16 v[52:55], v[100:103], v[8:11], v[52:55]
	ds_read_b128 v[96:99], v213 offset:17792
	s_waitcnt lgkmcnt(6)
	v_mfma_f32_16x16x32_bf16 v[48:51], v[104:107], v[12:15], v[48:51]
	ds_read_b128 v[100:103], v213 offset:52608
	s_waitcnt lgkmcnt(6)
	v_mfma_f32_16x16x32_bf16 v[52:55], v[108:111], v[12:15], v[52:55]
	ds_read_b128 v[104:107], v213 offset:17856
	s_waitcnt lgkmcnt(6)
	v_mfma_f32_16x16x32_bf16 v[48:51], v[80:83], v[16:19], v[48:51]
	ds_read_b128 v[108:111], v213 offset:52672
	s_waitcnt lgkmcnt(6)
	v_mfma_f32_16x16x32_bf16 v[52:55], v[84:87], v[16:19], v[52:55]
	ds_read_b128 v[80:83], v213 offset:26112
	s_waitcnt lgkmcnt(6)
	v_mfma_f32_16x16x32_bf16 v[48:51], v[88:91], v[20:23], v[48:51]
	ds_read_b128 v[84:87], v213 offset:60928
	s_waitcnt lgkmcnt(6)
	v_mfma_f32_16x16x32_bf16 v[52:55], v[92:95], v[20:23], v[52:55]
	ds_read_b128 v[88:91], v213 offset:26176
	s_waitcnt lgkmcnt(6)
	v_mfma_f32_16x16x32_bf16 v[48:51], v[96:99], v[24:27], v[48:51]
	ds_read_b128 v[92:95], v213 offset:60992
	s_waitcnt lgkmcnt(6)
	v_mfma_f32_16x16x32_bf16 v[52:55], v[100:103], v[24:27], v[52:55]
	ds_read_b128 v[96:99], v213 offset:26240
	s_waitcnt lgkmcnt(6)
	v_mfma_f32_16x16x32_bf16 v[48:51], v[104:107], v[28:31], v[48:51]
	ds_read_b128 v[100:103], v213 offset:61056
	s_waitcnt lgkmcnt(6)
	v_mfma_f32_16x16x32_bf16 v[52:55], v[108:111], v[28:31], v[52:55]
	ds_read_b128 v[104:107], v213 offset:26304
	s_waitcnt lgkmcnt(6)
	v_mfma_f32_16x16x32_bf16 v[56:59], v[80:83], v[0:3], 0
	ds_read_b128 v[108:111], v213 offset:61120
	s_waitcnt lgkmcnt(6)
	v_mfma_f32_16x16x32_bf16 v[60:63], v[84:87], v[0:3], 0
	ds_read_b128 v[80:83], v213 offset:26368
	s_waitcnt lgkmcnt(6)
	v_mfma_f32_16x16x32_bf16 v[56:59], v[88:91], v[4:7], v[56:59]
	ds_read_b128 v[84:87], v213 offset:61184
	s_waitcnt lgkmcnt(6)
	v_mfma_f32_16x16x32_bf16 v[60:63], v[92:95], v[4:7], v[60:63]
	ds_read_b128 v[88:91], v213 offset:26432
	s_waitcnt lgkmcnt(6)
	v_mfma_f32_16x16x32_bf16 v[56:59], v[96:99], v[8:11], v[56:59]
	ds_read_b128 v[92:95], v213 offset:61248
	s_waitcnt lgkmcnt(6)
	v_mfma_f32_16x16x32_bf16 v[60:63], v[100:103], v[8:11], v[60:63]
	ds_read_b128 v[96:99], v213 offset:26496
	s_waitcnt lgkmcnt(6)
	v_mfma_f32_16x16x32_bf16 v[56:59], v[104:107], v[12:15], v[56:59]
	ds_read_b128 v[100:103], v213 offset:61312
	s_waitcnt lgkmcnt(6)
	v_mfma_f32_16x16x32_bf16 v[60:63], v[108:111], v[12:15], v[60:63]
	ds_read_b128 v[64:67], v213 offset:26560
	s_waitcnt lgkmcnt(6)
	v_mfma_f32_16x16x32_bf16 v[56:59], v[80:83], v[16:19], v[56:59]
	ds_read_b128 v[68:71], v213 offset:61376
	s_waitcnt lgkmcnt(6)
	v_mfma_f32_16x16x32_bf16 v[60:63], v[84:87], v[16:19], v[60:63]
	s_waitcnt lgkmcnt(5)
	v_mfma_f32_16x16x32_bf16 v[56:59], v[88:91], v[20:23], v[56:59]
	s_waitcnt lgkmcnt(4)
	v_mfma_f32_16x16x32_bf16 v[60:63], v[92:95], v[20:23], v[60:63]
	s_waitcnt lgkmcnt(3)
	v_mfma_f32_16x16x32_bf16 v[56:59], v[96:99], v[24:27], v[56:59]
	s_waitcnt lgkmcnt(2)
	v_mfma_f32_16x16x32_bf16 v[60:63], v[100:103], v[24:27], v[60:63]
	s_waitcnt vmcnt(0)
	s_waitcnt lgkmcnt(1)
	v_mfma_f32_16x16x32_bf16 v[56:59], v[64:67], v[28:31], v[56:59]
	v_lshl_add_u64 v[64:65], s[58:59], 0, v[132:133]
	s_waitcnt lgkmcnt(0)
	s_barrier
	global_load_lds_dwordx4 v[64:65], off
	v_lshl_add_u64 v[64:65], s[60:61], 0, v[132:133]
	s_mov_b32 m0, s48
	v_mfma_f32_16x16x32_bf16 v[60:63], v[68:71], v[28:31], v[60:63]
	global_load_lds_dwordx4 v[64:65], off
	v_lshl_add_u64 v[64:65], s[58:59], 0, v[134:135]
	s_mov_b32 m0, s49
	s_nop 0
	global_load_lds_dwordx4 v[64:65], off
	v_lshl_add_u64 v[64:65], s[60:61], 0, v[134:135]
	s_mov_b32 m0, s62
	s_nop 0
	global_load_lds_dwordx4 v[64:65], off
	v_lshl_add_u64 v[64:65], s[58:59], 0, v[136:137]
	s_mov_b32 m0, s63
	s_nop 0
	global_load_lds_dwordx4 v[64:65], off
	v_lshl_add_u64 v[64:65], s[60:61], 0, v[136:137]
	s_mov_b32 m0, s64
	s_nop 0
	global_load_lds_dwordx4 v[64:65], off
	v_lshl_add_u64 v[64:65], s[58:59], 0, v[138:139]
	s_mov_b32 m0, s65
	s_nop 0
	global_load_lds_dwordx4 v[64:65], off
	v_lshl_add_u64 v[64:65], s[60:61], 0, v[138:139]
	s_mov_b32 m0, s66
	s_nop 0
	global_load_lds_dwordx4 v[64:65], off
	s_cbranch_vccnz .LBB0_1088
	s_mov_b32 m0, s82
	v_lshl_add_u64 v[66:67], s[58:59], 0, v[140:141]
	v_lshl_add_u64 v[64:65], s[60:61], 0, v[140:141]
	global_load_lds_dwordx4 v[66:67], off
	s_add_i32 m0, s82, 0x8800
	s_nop 0
	global_load_lds_dwordx4 v[64:65], off
